# q3 layer-0 weight conversion (both parity copies) by the hand-written prefetching transposer; smp_mlstm staging prefetch
# speedup vs baseline: 1.0196x; 1.0089x over previous
.LBB0_244:
	s_or_b64 exec, exec, s[68:69]
	s_lshl_b64 s[2:3], s[14:15], 10
	v_ashrrev_i32_e32 v6, 8, v0
	s_add_u32 s4, s18, s2
	v_mul_hi_i32_i24_e32 v3, 0x3600, v6
	v_mul_i32_i24_e32 v2, 0x3600, v6
	s_addc_u32 s5, s19, s3
	v_lshl_add_u64 v[2:3], s[28:29], 0, v[2:3]
	s_lshl_b32 s30, s84, 9
	v_lshl_add_u64 v[2:3], v[2:3], 0, s[30:31]
	v_lshlrev_b32_sdwa v168, v181, v0 dst_sel:DWORD dst_unused:UNUSED_PAD src0_sel:DWORD src1_sel:BYTE_0
	v_lshl_add_u64 v[2:3], v[2:3], 0, v[168:169]
	v_add_co_u32_e32 v248, vcc, 0x7400, v2
	s_nop 1
	v_addc_co_u32_e32 v249, vcc, 0, v3, vcc
	global_load_ushort v244, v[248:249], off offset:-2048
	global_load_ushort v244, v[248:249], off
	global_load_ushort v244, v[248:249], off offset:2048
	v_add_co_u32_e32 v248, vcc, 0x6c00, v248
	s_nop 1
	v_addc_co_u32_e32 v249, vcc, 0, v249, vcc
	global_load_ushort v244, v[248:249], off offset:-2048
	global_load_ushort v244, v[248:249], off
	global_load_ushort v244, v[248:249], off offset:2048
	v_add_co_u32_e32 v248, vcc, 0x6c00, v248
	s_nop 1
	v_addc_co_u32_e32 v249, vcc, 0, v249, vcc
	global_load_ushort v244, v[248:249], off offset:-2048
	global_load_ushort v244, v[248:249], off
	global_load_ushort v244, v[248:249], off offset:2048
	s_waitcnt lgkmcnt(0)
	s_barrier
	global_load_ushort v7, v[2:3], off
	global_load_ushort v8, v[2:3], off offset:2048
	v_add_co_u32_e32 v2, vcc, s63, v2
	v_lshlrev_b32_sdwa v4, v191, v0 dst_sel:DWORD dst_unused:UNUSED_PAD src0_sel:DWORD src1_sel:BYTE_0
	s_nop 0
	v_addc_co_u32_e32 v3, vcc, 0, v3, vcc
	global_load_ushort v2, v[2:3], off
	v_lshl_add_u32 v9, v0, 2, 0
	v_lshl_add_u32 v3, v6, 2, 0
	v_ashrrev_i32_e32 v128, 6, v0
	v_lshlrev_b32_e32 v13, 4, v36
	v_add_u32_e32 v37, 0, v13
	v_add_u32_e32 v1, 64, v1
	s_movk_i32 s2, 0xfc04
	s_waitcnt vmcnt(2)
	v_lshlrev_b32_e32 v7, 16, v7
	s_waitcnt vmcnt(1)
	v_lshlrev_b32_e32 v8, 16, v8
	s_waitcnt vmcnt(0)
	v_lshlrev_b32_e32 v2, 16, v2
	ds_write_b32 v9, v7
	ds_write_b32 v9, v8 offset:8192
	ds_write_b32 v9, v2 offset:16384
	v_add_u32_e32 v2, v4, v6
	v_lshl_add_u32 v2, v2, 2, 0
	ds_write_b32 v2, v7 offset:24576
	ds_read_b32 v3, v3 offset:41024
	s_waitcnt lgkmcnt(0)
	v_mul_f32_e32 v3, v3, v8
	ds_write_b32 v2, v3 offset:32768
	v_add_u32_e32 v2, 0x200, v0
	v_ashrrev_i32_e32 v6, 8, v2
	v_mul_hi_i32_i24_e32 v3, 0x3600, v6
	v_mul_i32_i24_e32 v2, 0x3600, v6
	v_lshl_add_u64 v[2:3], s[28:29], 0, v[2:3]
	v_lshl_add_u64 v[2:3], v[2:3], 0, s[30:31]
	v_lshl_add_u64 v[2:3], v[2:3], 0, v[168:169]
	global_load_ushort v7, v[2:3], off
	global_load_ushort v8, v[2:3], off offset:2048
	v_add_co_u32_e32 v2, vcc, s63, v2
	s_waitcnt vmcnt(1)
	v_lshlrev_b32_e32 v7, 16, v7
	v_addc_co_u32_e32 v3, vcc, 0, v3, vcc
	global_load_ushort v2, v[2:3], off
	s_waitcnt vmcnt(1)
	v_lshlrev_b32_e32 v8, 16, v8
	v_lshl_add_u32 v3, v6, 2, 0
	s_waitcnt vmcnt(0)
	v_lshlrev_b32_e32 v2, 16, v2
	ds_write_b32 v9, v7 offset:2048
	ds_write_b32 v9, v8 offset:10240
	ds_write_b32 v9, v2 offset:18432
	v_add_u32_e32 v2, v6, v4
	v_lshl_add_u32 v2, v2, 2, 0
	ds_write_b32 v2, v7 offset:24576
	ds_read_b32 v3, v3 offset:41024
	s_waitcnt lgkmcnt(0)
	v_mul_f32_e32 v3, v3, v8
	ds_write_b32 v2, v3 offset:32768
	v_add_u32_e32 v2, 0x400, v0
	v_ashrrev_i32_e32 v6, 8, v2
	v_mul_hi_i32_i24_e32 v3, 0x3600, v6
	v_mul_i32_i24_e32 v2, 0x3600, v6
	v_lshl_add_u64 v[2:3], s[28:29], 0, v[2:3]
	v_lshl_add_u64 v[2:3], v[2:3], 0, s[30:31]
	v_lshl_add_u64 v[2:3], v[2:3], 0, v[168:169]
	global_load_ushort v7, v[2:3], off
	global_load_ushort v8, v[2:3], off offset:2048
	v_add_co_u32_e32 v2, vcc, s63, v2
	s_waitcnt vmcnt(1)
	v_lshlrev_b32_e32 v7, 16, v7
	v_addc_co_u32_e32 v3, vcc, 0, v3, vcc
	global_load_ushort v2, v[2:3], off
	s_waitcnt vmcnt(1)
	v_lshlrev_b32_e32 v8, 16, v8
	v_lshl_add_u32 v3, v6, 2, 0
	s_waitcnt vmcnt(0)
	v_lshlrev_b32_e32 v2, 16, v2
	ds_write_b32 v9, v7 offset:4096
	ds_write_b32 v9, v8 offset:12288
	ds_write_b32 v9, v2 offset:20480
	v_add_u32_e32 v2, v6, v4
	v_lshl_add_u32 v2, v2, 2, 0
	ds_write_b32 v2, v7 offset:24576
	ds_read_b32 v3, v3 offset:41024
	s_waitcnt lgkmcnt(0)
	v_mul_f32_e32 v3, v3, v8
	ds_write_b32 v2, v3 offset:32768
	v_add_u32_e32 v2, 0x600, v0
	v_ashrrev_i32_e32 v6, 8, v2
	v_mul_hi_i32_i24_e32 v3, 0x3600, v6
	v_mul_i32_i24_e32 v2, 0x3600, v6
	v_lshl_add_u64 v[2:3], s[28:29], 0, v[2:3]
	v_lshl_add_u64 v[2:3], v[2:3], 0, s[30:31]
	v_lshl_add_u64 v[2:3], v[2:3], 0, v[168:169]
	global_load_ushort v7, v[2:3], off
	global_load_ushort v8, v[2:3], off offset:2048
	v_add_co_u32_e32 v2, vcc, s63, v2
	s_waitcnt vmcnt(1)
	v_lshlrev_b32_e32 v7, 16, v7
	v_addc_co_u32_e32 v3, vcc, 0, v3, vcc
	global_load_ushort v2, v[2:3], off
	s_waitcnt vmcnt(1)
	v_lshlrev_b32_e32 v8, 16, v8
	v_lshl_add_u32 v3, v6, 2, 0
	s_waitcnt vmcnt(0)
	v_lshlrev_b32_e32 v2, 16, v2
	ds_write_b32 v9, v7 offset:6144
	ds_write_b32 v9, v8 offset:14336
	ds_write_b32 v9, v2 offset:22528
	v_add_u32_e32 v2, v6, v4
	v_lshl_add_u32 v2, v2, 2, 0
	ds_write_b32 v2, v7 offset:24576
	ds_read_b32 v3, v3 offset:41024
	s_waitcnt lgkmcnt(0)
	v_mul_f32_e32 v3, v3, v8
	ds_write_b32 v2, v3 offset:32768
	v_lshl_add_u32 v2, v128, 10, 0
	v_add_u32_e32 v140, v2, v13
	s_waitcnt lgkmcnt(0)
	s_barrier
	ds_read_b128 v[14:17], v140
	ds_read_b128 v[6:9], v37 offset:8192
	ds_read_b128 v[18:21], v37 offset:11264
	s_waitcnt lgkmcnt(1)
	v_mul_f32_e32 v12, v15, v7
	v_fmac_f32_e32 v12, v14, v6
	v_fmac_f32_e32 v12, v16, v8
	v_fmac_f32_e32 v12, v17, v9
	ds_read_b128 v[6:9], v37 offset:9216
	s_waitcnt lgkmcnt(0)
	v_mul_f32_e32 v11, v15, v7
	v_fmac_f32_e32 v11, v14, v6
	v_fmac_f32_e32 v11, v16, v8
	v_fmac_f32_e32 v11, v17, v9
	ds_read_b128 v[6:9], v37 offset:10240
	s_waitcnt lgkmcnt(0)
	v_mul_f32_e32 v10, v15, v7
	v_fmac_f32_e32 v10, v14, v6
	v_fmac_f32_e32 v10, v16, v8
	v_fmac_f32_e32 v10, v17, v9
	v_mul_f32_e32 v9, v15, v19
	v_fmac_f32_e32 v9, v14, v18
	v_fmac_f32_e32 v9, v16, v20
	v_fmac_f32_e32 v9, v17, v21
	ds_read_b128 v[18:21], v37 offset:12288
	s_waitcnt lgkmcnt(0)
	v_mul_f32_e32 v8, v15, v19
	v_fmac_f32_e32 v8, v14, v18
	v_fmac_f32_e32 v8, v16, v20
	v_fmac_f32_e32 v8, v17, v21
	ds_read_b128 v[18:21], v37 offset:13312
	s_waitcnt lgkmcnt(0)
	v_mul_f32_e32 v6, v15, v19
	v_fmac_f32_e32 v6, v14, v18
	v_fmac_f32_e32 v6, v16, v20
	v_fmac_f32_e32 v6, v17, v21
	ds_read_b128 v[18:21], v37 offset:14336
	s_waitcnt lgkmcnt(0)
	v_mul_f32_e32 v4, v15, v19
	v_fmac_f32_e32 v4, v14, v18
	v_fmac_f32_e32 v4, v16, v20
	v_fmac_f32_e32 v4, v17, v21
	ds_read_b128 v[18:21], v37 offset:15360
	s_waitcnt lgkmcnt(0)
	v_mul_f32_e32 v3, v15, v19
	v_fmac_f32_e32 v3, v14, v18
	v_fmac_f32_e32 v3, v16, v20
	v_fmac_f32_e32 v3, v17, v21
	global_load_dwordx4 v[18:21], v13, s[4:5]
	v_xor_b32_e32 v13, 32, v5
	v_cmp_lt_i32_e32 vcc, v13, v1
	s_waitcnt vmcnt(0)
	v_mul_f32_e32 v7, v15, v19
	v_cndmask_b32_e32 v13, v5, v13, vcc
	v_fmac_f32_e32 v7, v14, v18
	v_lshlrev_b32_e32 v141, 2, v13
	v_fmac_f32_e32 v7, v16, v20
	ds_bpermute_b32 v16, v141, v6
	v_xor_b32_e32 v13, 16, v5
	v_cmp_lt_i32_e32 vcc, v13, v1
	v_fmac_f32_e32 v7, v17, v21
	ds_bpermute_b32 v14, v141, v9
	v_cndmask_b32_e32 v13, v5, v13, vcc
	v_lshlrev_b32_e32 v142, 2, v13
	s_waitcnt lgkmcnt(1)
	v_add_f32_e32 v6, v6, v16
	ds_bpermute_b32 v16, v142, v6
	v_xor_b32_e32 v13, 8, v5
	v_cmp_lt_i32_e32 vcc, v13, v1
	ds_bpermute_b32 v15, v141, v8
	s_waitcnt lgkmcnt(2)
	v_add_f32_e32 v9, v9, v14
	v_cndmask_b32_e32 v13, v5, v13, vcc
	v_lshlrev_b32_e32 v143, 2, v13
	s_waitcnt lgkmcnt(1)
	v_add_f32_e32 v6, v6, v16
	ds_bpermute_b32 v16, v143, v6
	v_xor_b32_e32 v13, 4, v5
	v_cmp_lt_i32_e32 vcc, v13, v1
	s_waitcnt lgkmcnt(1)
	v_add_f32_e32 v8, v8, v15
	ds_bpermute_b32 v14, v142, v9
	v_cndmask_b32_e32 v13, v5, v13, vcc
	v_lshlrev_b32_e32 v144, 2, v13
	s_waitcnt lgkmcnt(1)
	v_add_f32_e32 v6, v6, v16
	ds_bpermute_b32 v16, v144, v6
	v_xor_b32_e32 v13, 2, v5
	v_cmp_lt_i32_e32 vcc, v13, v1
	ds_bpermute_b32 v15, v142, v8
	s_waitcnt lgkmcnt(2)
	v_add_f32_e32 v9, v9, v14
	v_cndmask_b32_e32 v13, v5, v13, vcc
	v_lshlrev_b32_e32 v145, 2, v13
	s_waitcnt lgkmcnt(1)
	v_add_f32_e32 v6, v6, v16
	ds_bpermute_b32 v16, v145, v6
	v_xor_b32_e32 v13, 1, v5
	v_cmp_lt_i32_e32 vcc, v13, v1
	s_waitcnt lgkmcnt(1)
	v_add_f32_e32 v8, v8, v15
	ds_bpermute_b32 v14, v143, v9
	s_waitcnt lgkmcnt(1)
	v_add_f32_e32 v18, v6, v16
	ds_bpermute_b32 v16, v141, v3
	v_cndmask_b32_e32 v1, v5, v13, vcc
	v_lshlrev_b32_e32 v146, 2, v1
	ds_bpermute_b32 v1, v141, v12
	ds_bpermute_b32 v13, v141, v10
	s_waitcnt lgkmcnt(2)
	v_add_f32_e32 v3, v3, v16
	ds_bpermute_b32 v16, v142, v3
	ds_bpermute_b32 v6, v141, v4
	s_waitcnt lgkmcnt(3)
	v_add_f32_e32 v1, v12, v1
	ds_bpermute_b32 v12, v141, v11
	s_waitcnt lgkmcnt(3)
	v_add_f32_e32 v10, v10, v13
	s_waitcnt lgkmcnt(2)
	v_add_f32_e32 v3, v3, v16
	ds_bpermute_b32 v16, v143, v3
	s_waitcnt lgkmcnt(2)
	v_add_f32_e32 v4, v4, v6
	s_waitcnt lgkmcnt(1)
	v_add_f32_e32 v11, v11, v12
	ds_bpermute_b32 v5, v142, v1
	ds_bpermute_b32 v12, v142, v11
	s_waitcnt lgkmcnt(2)
	v_add_f32_e32 v3, v3, v16
	ds_bpermute_b32 v16, v144, v3
	ds_bpermute_b32 v13, v142, v10
	ds_bpermute_b32 v6, v142, v4
	s_waitcnt lgkmcnt(4)
	v_add_f32_e32 v1, v1, v5
	s_waitcnt lgkmcnt(3)
	v_add_f32_e32 v11, v11, v12
	s_waitcnt lgkmcnt(2)
	v_add_f32_e32 v3, v3, v16
	ds_bpermute_b32 v16, v145, v3
	s_waitcnt lgkmcnt(2)
	v_add_f32_e32 v10, v10, v13
	s_waitcnt lgkmcnt(1)
	v_add_f32_e32 v4, v4, v6
	ds_bpermute_b32 v5, v143, v1
	ds_bpermute_b32 v12, v143, v11
	s_waitcnt lgkmcnt(2)
	v_add_f32_e32 v16, v3, v16
	ds_bpermute_b32 v3, v141, v7
	ds_bpermute_b32 v13, v143, v10
	ds_bpermute_b32 v15, v143, v8
	ds_bpermute_b32 v6, v143, v4
	s_waitcnt lgkmcnt(5)
	v_add_f32_e32 v1, v1, v5
	s_waitcnt lgkmcnt(3)
	v_add_f32_e32 v3, v7, v3
	ds_bpermute_b32 v7, v142, v3
	v_add_f32_e32 v11, v11, v12
	s_waitcnt lgkmcnt(3)
	v_add_f32_e32 v10, v10, v13
	v_add_f32_e32 v9, v9, v14
	s_waitcnt lgkmcnt(2)
	v_add_f32_e32 v8, v8, v15
	s_waitcnt lgkmcnt(0)
	v_add_f32_e32 v3, v3, v7
	ds_bpermute_b32 v7, v143, v3
	v_add_f32_e32 v4, v4, v6
	ds_bpermute_b32 v5, v144, v1
	ds_bpermute_b32 v12, v144, v11
	ds_bpermute_b32 v13, v144, v10
	s_waitcnt lgkmcnt(3)
	v_add_f32_e32 v3, v3, v7
	ds_bpermute_b32 v14, v144, v9
	ds_bpermute_b32 v15, v144, v8
	ds_bpermute_b32 v6, v144, v4
	ds_bpermute_b32 v7, v144, v3
	s_waitcnt lgkmcnt(6)
	v_add_f32_e32 v1, v1, v5
	s_waitcnt lgkmcnt(5)
	v_add_f32_e32 v11, v11, v12
	s_waitcnt lgkmcnt(4)
	v_add_f32_e32 v10, v10, v13
	s_waitcnt lgkmcnt(3)
	v_add_f32_e32 v9, v9, v14
	s_waitcnt lgkmcnt(2)
	v_add_f32_e32 v8, v8, v15
	s_waitcnt lgkmcnt(1)
	v_add_f32_e32 v4, v4, v6
	s_waitcnt lgkmcnt(0)
	v_add_f32_e32 v3, v3, v7
	ds_bpermute_b32 v5, v145, v1
	ds_bpermute_b32 v12, v145, v11
	ds_bpermute_b32 v13, v145, v10
	ds_bpermute_b32 v14, v145, v9
	ds_bpermute_b32 v15, v145, v8
	ds_bpermute_b32 v6, v145, v4
	ds_bpermute_b32 v7, v145, v3
	s_waitcnt lgkmcnt(6)
	v_add_f32_e32 v1, v1, v5
	s_waitcnt lgkmcnt(5)
	v_add_f32_e32 v11, v11, v12
	s_waitcnt lgkmcnt(4)
	v_add_f32_e32 v10, v10, v13
	s_waitcnt lgkmcnt(3)
	v_add_f32_e32 v9, v9, v14
	s_waitcnt lgkmcnt(2)
	v_add_f32_e32 v8, v8, v15
	s_waitcnt lgkmcnt(1)
	v_add_f32_e32 v4, v4, v6
	s_waitcnt lgkmcnt(0)
	v_add_f32_e32 v7, v3, v7
	ds_bpermute_b32 v5, v146, v1
	ds_bpermute_b32 v12, v146, v11
	ds_bpermute_b32 v13, v146, v10
	ds_bpermute_b32 v14, v146, v9
	ds_bpermute_b32 v15, v146, v8
	ds_bpermute_b32 v19, v146, v18
	ds_bpermute_b32 v6, v146, v4
	ds_bpermute_b32 v17, v146, v16
	ds_bpermute_b32 v20, v146, v7
	v_mad_u64_u32 v[2:3], s[2:3], v128, s2, v[2:3]
	v_cmp_lt_i32_e32 vcc, -1, v128
	v_mov_b32_e32 v3, 0
	v_add_u32_e32 v147, 0xa000, v2
	s_and_saveexec_b64 s[2:3], vcc
	s_cbranch_execz .LBB0_246
	ds_read2_b32 v[22:23], v147 offset0:32 offset1:48
	s_waitcnt lgkmcnt(9)
	v_add_f32_e32 v1, v1, v5
	ds_read_b32 v5, v169 offset:41120
	s_waitcnt lgkmcnt(1)
	v_sub_f32_e32 v3, v23, v22
	s_waitcnt lgkmcnt(0)
	v_add_f32_e32 v3, v3, v5
	v_mul_f32_e32 v3, 0x3fb8aa3b, v3
	v_exp_f32_e32 v3, v3
	s_nop 0
	v_mul_f32_e32 v3, v1, v3

.LBB0_567:
	s_or_b64 exec, exec, s[2:3]
	v_readlane_b32 s2, v241, 9
	v_readlane_b32 s68, v241, 0
	s_mov_b32 s69, s2
	s_waitcnt lgkmcnt(0)
	s_barrier
	v_readlane_b32 s3, v241, 10
	s_cmpk_eq_i32 s69, 0x100
	v_readlane_b32 s4, v239, 40
	s_cselect_b64 s[2:3], -1, 0
	v_readlane_b32 s5, v239, 41
	s_and_b64 s[78:79], s[4:5], s[2:3]
	s_bitcmp1_b32 s68, 0
	s_cselect_b64 s[82:83], -1, 0
	s_cmpk_lt_i32 s68, 0x1220
	s_cselect_b64 s[84:85], -1, 0
	s_and_b64 s[2:3], s[84:85], s[82:83]
	s_and_b64 s[2:3], s[78:79], s[2:3]
	s_andn2_b64 vcc, exec, s[2:3]
	s_cbranch_vccnz .LBB0_590
	s_mov_b32 s70, s68
	s_mov_b32 s8, 0
	v_readlane_b32 s14, v239, 42
	v_readlane_b32 s15, v239, 43
	v_lshrrev_b32_e32 v117, 5, v178
	v_and_b32_e32 v168, 31, v178
	v_lshlrev_b32_e32 v116, 2, v168
	v_mul_u32_u24_e32 v16, 0x204, v117
	v_lshl_add_u32 v16, v116, 2, v16
	v_and_b32_e32 v168, 7, v178
	v_lshlrev_b32_e32 v120, 4, v168
	v_mul_u32_u24_e32 v17, 0x1020, v168
	v_lshrrev_b32_e32 v119, 3, v178
	v_lshl_add_u32 v17, v119, 2, v17
	s_add_i32 s4, s70, 1728
	s_mov_b32 s39, 0
	s_cmpk_lt_u32 s4, 0x6c0
	s_cbranch_scc0 .Ltrq3a_t1_0
	s_lshr_b32 s5, s4, 5
	s_and_b32 s6, s4, 31
	v_readlane_b32 s28, v241, 11
	v_readlane_b32 s29, v241, 12
	s_mul_i32 s9, s8, 0x3430000
	s_movk_i32 s38, 0x6860
	s_mov_b32 s2, 0
	s_mul_i32 s3, s8, 0x1b00000
	s_movk_i32 s44, 0x1000
	s_mov_b32 s39, 1
	s_branch .Ltrq3a_dec_0
.Ltrq3a_t1_0:
	s_sub_i32 s4, s4, 0x6c0
	s_cmpk_lt_u32 s4, 0x200
	s_cbranch_scc0 .Ltrq3a_t2_0
	s_lshr_b32 s5, s4, 5
	s_and_b32 s6, s4, 31
	v_readlane_b32 s28, v241, 31
	v_readlane_b32 s29, v241, 32
	s_lshl_b32 s9, s8, 24
	s_movk_i32 s38, 0x2000
	s_mov_b32 s2, 0x3600000
	s_lshl_b32 s3, s8, 23
	s_movk_i32 s44, 0x1000
	s_branch .Ltrq3a_dec_0
.Ltrq3a_t2_0:
	s_sub_i32 s4, s4, 0x200
	s_cmpk_lt_u32 s4, 0xac0
	s_cbranch_scc0 .Ltrq3a_t3_0
	s_lshr_b32 s5, s4, 5
	s_and_b32 s6, s4, 31
	v_readlane_b32 s28, v241, 37
	v_readlane_b32 s29, v241, 38
	s_mul_i32 s9, s8, 0x5600000
	s_mov_b32 s38, 0xac00
	s_mov_b32 s2, 0x4600000
	s_mul_i32 s3, s8, 0x2b00000
	s_movk_i32 s44, 0x1000
	s_branch .Ltrq3a_dec_0
.Ltrq3a_t3_0:
	s_sub_i32 s4, s4, 0xac0
	s_mul_hi_u32 s5, s4, 0x2fa0be9
	s_mul_i32 s6, s5, 86
	s_sub_i32 s6, s4, s6
	v_readlane_b32 s28, v241, 1
	v_readlane_b32 s29, v241, 2
	s_mul_i32 s9, s8, 0x2b00000
	s_movk_i32 s38, 0x2000
	s_mov_b32 s2, 0x9c00000
	s_mul_i32 s3, s8, 0x1580000
	s_movk_i32 s44, 0x2b00
.Ltrq3a_dec_0:
	s_add_u32 s28, s28, s9
	s_addc_u32 s29, s29, 0
	s_lshl_b32 s40, s5, 7
	s_lshl_b32 s9, s6, 6
	s_mul_i32 s9, s9, s38
	s_add_u32 s36, s28, s9
	s_addc_u32 s37, s29, 0
	s_add_u32 s42, s14, s2
	s_addc_u32 s43, s15, 0
	s_add_u32 s42, s42, s3
	s_addc_u32 s43, s43, 0
	s_mul_i32 s9, s40, s44
	s_lshl_b32 s2, s6, 7
	s_add_u32 s9, s9, s2
	s_add_u32 s42, s42, s9
	s_addc_u32 s43, s43, 0
	s_lshr_b32 s9, s40, 10
	s_cmp_eq_u32 s9, 1
	s_cselect_b32 s45, s39, 0
	v_add_u32_e32 v19, s40, v116
	s_mov_b64 s[12:13], 0
	s_cmp_eq_u32 s39, 0
	s_cbranch_scc1 .Ltrq3a_m0_1
	v_add_u32_e32 v168, 8, v19
	v_cmp_gt_u32_e32 vcc, 0x1000, v19
	s_nop 1
	v_cndmask_b32_e32 v168, v168, v19, vcc
	v_add_u32_e32 v118, 0xfffff600, v19
	v_cmp_gt_u32_e32 vcc, 0x1a00, v19
	s_nop 1
	v_cndmask_b32_e32 v168, v118, v168, vcc
	v_cmp_gt_u32_e32 vcc, 0x1a08, v19
	s_nop 1
	v_cndmask_b32_e32 v168, v19, v168, vcc
	s_movk_i32 s9, 0x1a18
	v_cmp_le_u32_e64 s[12:13], s9, v19
	s_nop 1
	v_cndmask_b32_e64 v19, v168, 0, s[12:13]
.Ltrq3a_m0_1:
	v_lshlrev_b32_e32 v19, 2, v19
	v_mad_u32_u24 v18, v117, s38, v19
	s_lshl_b32 s9, s38, 4
	global_load_dwordx4 v[100:103], v18, s[36:37] nt
	s_add_u32 s36, s36, s9
	s_addc_u32 s37, s37, 0
	global_load_dwordx4 v[104:107], v18, s[36:37] nt
	s_add_u32 s36, s36, s9
	s_addc_u32 s37, s37, 0
	global_load_dwordx4 v[108:111], v18, s[36:37] nt
	s_add_u32 s36, s36, s9
	s_addc_u32 s37, s37, 0
	global_load_dwordx4 v[112:115], v18, s[36:37] nt
	s_waitcnt vmcnt(0)
.Ltrq3a_top:
	s_mov_b64 s[46:47], s[42:43]
	s_mov_b32 s48, s44
	s_mov_b32 s49, s45
	s_mov_b64 s[50:51], s[12:13]
	v_mad_u32_u24 v20, v119, s48, v120
	s_lshl_b32 s9, s48, 6
	v_add_u32_e32 v21, s9, v20
	s_waitcnt vmcnt(2)
	v_cndmask_b32_e64 v100, v100, 0, s[50:51]
	v_cndmask_b32_e64 v101, v101, 0, s[50:51]
	v_cndmask_b32_e64 v102, v102, 0, s[50:51]
	v_cndmask_b32_e64 v103, v103, 0, s[50:51]
	v_cndmask_b32_e64 v104, v104, 0, s[50:51]
	v_cndmask_b32_e64 v105, v105, 0, s[50:51]
	v_cndmask_b32_e64 v106, v106, 0, s[50:51]
	v_cndmask_b32_e64 v107, v107, 0, s[50:51]
	v_cndmask_b32_e64 v108, v108, 0, s[50:51]
	v_cndmask_b32_e64 v109, v109, 0, s[50:51]
	v_cndmask_b32_e64 v110, v110, 0, s[50:51]
	v_cndmask_b32_e64 v111, v111, 0, s[50:51]
	v_cndmask_b32_e64 v112, v112, 0, s[50:51]
	v_cndmask_b32_e64 v113, v113, 0, s[50:51]
	v_cndmask_b32_e64 v114, v114, 0, s[50:51]
	v_cndmask_b32_e64 v115, v115, 0, s[50:51]
	s_cmp_eq_u32 s49, 0
	s_cbranch_scc1 .Ltrq3a_nosc
	v_mul_f32_e32 v100, 0x3d800000, v100
	v_mul_f32_e32 v101, 0x3d800000, v101
	v_mul_f32_e32 v102, 0x3d800000, v102
	v_mul_f32_e32 v103, 0x3d800000, v103
	v_mul_f32_e32 v104, 0x3d800000, v104
	v_mul_f32_e32 v105, 0x3d800000, v105
	v_mul_f32_e32 v106, 0x3d800000, v106
	v_mul_f32_e32 v107, 0x3d800000, v107
	v_mul_f32_e32 v108, 0x3d800000, v108
	v_mul_f32_e32 v109, 0x3d800000, v109
	v_mul_f32_e32 v110, 0x3d800000, v110
	v_mul_f32_e32 v111, 0x3d800000, v111
	v_mul_f32_e32 v112, 0x3d800000, v112
	v_mul_f32_e32 v113, 0x3d800000, v113
	v_mul_f32_e32 v114, 0x3d800000, v114
	v_mul_f32_e32 v115, 0x3d800000, v115
.Ltrq3a_nosc:
	v_mov_b32_e32 v168, v16
	ds_write2_b32 v168, v100, v101 offset1:1
	ds_write2_b32 v168, v102, v103 offset0:2 offset1:3
	v_add_u32_e32 v168, 8256, v16
	ds_write2_b32 v168, v104, v105 offset1:1
	ds_write2_b32 v168, v106, v107 offset0:2 offset1:3
	v_add_u32_e32 v168, 16512, v16
	ds_write2_b32 v168, v108, v109 offset1:1
	ds_write2_b32 v168, v110, v111 offset0:2 offset1:3
	v_add_u32_e32 v168, 24768, v16
	ds_write2_b32 v168, v112, v113 offset1:1
	ds_write2_b32 v168, v114, v115 offset0:2 offset1:3
	s_add_i32 s70, s70, 256
	s_cmpk_lt_u32 s70, 0x1220
	s_cselect_b32 s7, 1, 0
	s_cbranch_scc0 .Ltrq3a_nonext
	s_add_i32 s4, s70, 1728
	s_mov_b32 s39, 0
	s_cmpk_lt_u32 s4, 0x6c0
	s_cbranch_scc0 .Ltrq3a_t1_1
	s_lshr_b32 s5, s4, 5
	s_and_b32 s6, s4, 31
	v_readlane_b32 s28, v241, 11
	v_readlane_b32 s29, v241, 12
	s_mul_i32 s9, s8, 0x3430000
	s_movk_i32 s38, 0x6860
	s_mov_b32 s2, 0
	s_mul_i32 s3, s8, 0x1b00000
	s_movk_i32 s44, 0x1000
	s_mov_b32 s39, 1
	s_branch .Ltrq3a_dec_1

.Ltrq3a_m0_2:
	v_lshlrev_b32_e32 v19, 2, v19
	v_mad_u32_u24 v18, v117, s38, v19
	s_lshl_b32 s9, s38, 4
	global_load_dwordx4 v[100:103], v18, s[36:37] nt
	s_add_u32 s36, s36, s9
	s_addc_u32 s37, s37, 0
	global_load_dwordx4 v[104:107], v18, s[36:37] nt
	s_add_u32 s36, s36, s9
	s_addc_u32 s37, s37, 0
	global_load_dwordx4 v[108:111], v18, s[36:37] nt
	s_add_u32 s36, s36, s9
	s_addc_u32 s37, s37, 0
	global_load_dwordx4 v[112:115], v18, s[36:37] nt
.Ltrq3a_nonext:
	s_waitcnt lgkmcnt(0)
	s_barrier
	ds_read_b32 v0, v17
	ds_read_b32 v1, v17 offset:516
	ds_read_b32 v2, v17 offset:1032
	ds_read_b32 v3, v17 offset:1548
	ds_read_b32 v4, v17 offset:2064
	ds_read_b32 v5, v17 offset:2580
	ds_read_b32 v6, v17 offset:3096
	ds_read_b32 v7, v17 offset:3612
	ds_read_b32 v8, v17 offset:256
	ds_read_b32 v9, v17 offset:772
	ds_read_b32 v10, v17 offset:1288
	ds_read_b32 v11, v17 offset:1804
	ds_read_b32 v12, v17 offset:2320
	ds_read_b32 v13, v17 offset:2836
	ds_read_b32 v14, v17 offset:3352
	ds_read_b32 v15, v17 offset:3868
	s_waitcnt lgkmcnt(8)
	v_cvt_pk_bf16_f32 v0, v0, v1
	v_cvt_pk_bf16_f32 v1, v2, v3
	v_cvt_pk_bf16_f32 v2, v4, v5
	v_cvt_pk_bf16_f32 v3, v6, v7
	global_store_dwordx4 v20, v[0:3], s[46:47]
	s_waitcnt lgkmcnt(0)
	v_cvt_pk_bf16_f32 v8, v8, v9
	v_cvt_pk_bf16_f32 v9, v10, v11
	v_cvt_pk_bf16_f32 v10, v12, v13
	v_cvt_pk_bf16_f32 v11, v14, v15
	global_store_dwordx4 v21, v[8:11], s[46:47]
	s_barrier
	s_cmp_lg_u32 s7, 0
	s_cbranch_scc1 .Ltrq3a_top
	s_branch .LBB0_590
.LBB0_590:
	s_cmpk_gt_i32 s68, 0x1ff
	s_cbranch_scc1 .LBB0_647
	s_add_i32 s86, s68, -1
	s_mov_b32 s88, s68
	s_branch .LBB0_593

.LBB0_918:
	s_xor_b64 s[2:3], s[82:83], -1
	s_and_b64 s[2:3], s[78:79], s[2:3]
	s_and_b64 s[2:3], s[2:3], s[84:85]
	s_andn2_b64 vcc, exec, s[2:3]
	s_cbranch_vccnz .LBB0_941
	s_mov_b32 s8, 0
	v_readlane_b32 s14, v239, 42
	v_readlane_b32 s15, v239, 43
	v_lshrrev_b32_e32 v117, 5, v178
	v_and_b32_e32 v168, 31, v178
	v_lshlrev_b32_e32 v116, 2, v168
	v_mul_u32_u24_e32 v16, 0x204, v117
	v_lshl_add_u32 v16, v116, 2, v16
	v_and_b32_e32 v168, 7, v178
	v_lshlrev_b32_e32 v120, 4, v168
	v_mul_u32_u24_e32 v17, 0x1020, v168
	v_lshrrev_b32_e32 v119, 3, v178
	v_lshl_add_u32 v17, v119, 2, v17
	s_add_i32 s4, s68, 1728
	s_mov_b32 s39, 0
	s_cmpk_lt_u32 s4, 0x6c0
	s_cbranch_scc0 .Ltrq3b_t1_0
	s_lshr_b32 s5, s4, 5
	s_and_b32 s6, s4, 31
	v_readlane_b32 s28, v241, 11
	v_readlane_b32 s29, v241, 12
	s_mul_i32 s9, s8, 0x3430000
	s_movk_i32 s38, 0x6860
	s_mov_b32 s2, 0
	s_mul_i32 s3, s8, 0x1b00000
	s_movk_i32 s44, 0x1000
	s_mov_b32 s39, 1
	s_branch .Ltrq3b_dec_0

.Ltrq3b_nosc:
	v_mov_b32_e32 v168, v16
	ds_write2_b32 v168, v100, v101 offset1:1
	ds_write2_b32 v168, v102, v103 offset0:2 offset1:3
	v_add_u32_e32 v168, 8256, v16
	ds_write2_b32 v168, v104, v105 offset1:1
	ds_write2_b32 v168, v106, v107 offset0:2 offset1:3
	v_add_u32_e32 v168, 16512, v16
	ds_write2_b32 v168, v108, v109 offset1:1
	ds_write2_b32 v168, v110, v111 offset0:2 offset1:3
	v_add_u32_e32 v168, 24768, v16
	ds_write2_b32 v168, v112, v113 offset1:1
	ds_write2_b32 v168, v114, v115 offset0:2 offset1:3
	s_add_i32 s68, s68, 256
	s_cmpk_lt_u32 s68, 0x1220
	s_cselect_b32 s7, 1, 0
	s_cbranch_scc0 .Ltrq3b_nonext
	s_add_i32 s4, s68, 1728
	s_mov_b32 s39, 0
	s_cmpk_lt_u32 s4, 0x6c0
	s_cbranch_scc0 .Ltrq3b_t1_1
	s_lshr_b32 s5, s4, 5
	s_and_b32 s6, s4, 31
	v_readlane_b32 s28, v241, 11
	v_readlane_b32 s29, v241, 12
	s_mul_i32 s9, s8, 0x3430000
	s_movk_i32 s38, 0x6860
	s_mov_b32 s2, 0
	s_mul_i32 s3, s8, 0x1b00000
	s_movk_i32 s44, 0x1000
	s_mov_b32 s39, 1
	s_branch .Ltrq3b_dec_1

.Ltrq3b_nonext:
	s_waitcnt lgkmcnt(0)
	s_barrier
	ds_read_b32 v0, v17
	ds_read_b32 v1, v17 offset:516
	ds_read_b32 v2, v17 offset:1032
	ds_read_b32 v3, v17 offset:1548
	ds_read_b32 v4, v17 offset:2064
	ds_read_b32 v5, v17 offset:2580
	ds_read_b32 v6, v17 offset:3096
	ds_read_b32 v7, v17 offset:3612
	ds_read_b32 v8, v17 offset:256
	ds_read_b32 v9, v17 offset:772
	ds_read_b32 v10, v17 offset:1288
	ds_read_b32 v11, v17 offset:1804
	ds_read_b32 v12, v17 offset:2320
	ds_read_b32 v13, v17 offset:2836
	ds_read_b32 v14, v17 offset:3352
	ds_read_b32 v15, v17 offset:3868
	s_waitcnt lgkmcnt(8)
	v_cvt_pk_bf16_f32 v0, v0, v1
	v_cvt_pk_bf16_f32 v1, v2, v3
	v_cvt_pk_bf16_f32 v2, v4, v5
	v_cvt_pk_bf16_f32 v3, v6, v7
	global_store_dwordx4 v20, v[0:3], s[46:47]
	s_waitcnt lgkmcnt(0)
	v_cvt_pk_bf16_f32 v8, v8, v9
	v_cvt_pk_bf16_f32 v9, v10, v11
	v_cvt_pk_bf16_f32 v10, v12, v13
	v_cvt_pk_bf16_f32 v11, v14, v15
	global_store_dwordx4 v21, v[8:11], s[46:47]
	s_barrier
	s_cmp_lg_u32 s7, 0
	s_cbranch_scc1 .Ltrq3b_top
	s_branch .LBB0_941
.LBB0_941:
	s_getreg_b32 s4, hwreg(HW_REG_XCC_ID, 0, 4)
	s_waitcnt vmcnt(0)
	s_barrier
	s_mov_b64 s[2:3], exec
	v_readlane_b32 s6, v241, 45
	v_readlane_b32 s7, v241, 46
	s_and_b64 s[6:7], s[2:3], s[6:7]
	s_mov_b64 exec, s[6:7]
	s_cbranch_execz .LBB0_993
	v_readlane_b32 s5, v239, 30
	s_waitcnt vmcnt(0) expcnt(0) lgkmcnt(0)
	s_and_b32 s12, s4, 15
	v_mov_b32_e32 v0, s5
	ds_read_b32 v2, v0
	v_readlane_b32 s5, v239, 31
	s_waitcnt lgkmcnt(0)
	v_cmp_ne_u32_e32 vcc, 0, v2
	v_mov_b32_e32 v0, s5
	ds_read_b32 v0, v0
	s_cbranch_vccnz .LBB0_957
	s_mov_b32 s13, 1
	s_branch .LBB0_945

.LBB0_1194:
	s_cmpk_eq_i32 s72, 0x100
	v_readlane_b32 s4, v239, 40
	s_cselect_b64 s[2:3], -1, 0
	v_readlane_b32 s5, v239, 41
	s_and_b64 s[2:3], s[4:5], s[2:3]
	s_cmp_gt_i32 s58, 11
	s_cselect_b64 s[4:5], -1, 0
	s_and_b64 s[2:3], s[2:3], s[4:5]
	s_add_i32 s8, s58, -12
	s_cmpk_lt_u32 s8, 0x18e0
	s_cselect_b64 s[4:5], -1, 0
	s_and_b64 s[2:3], s[2:3], s[4:5]
	v_readlane_b32 s72, v241, 47
	s_andn2_b64 vcc, exec, s[2:3]
	v_readlane_b32 s73, v241, 48
	s_cbranch_vccnz .LBB0_1217
	s_mov_b32 s56, s8
	s_mov_b32 s8, 1
	v_readlane_b32 s14, v239, 42
	v_readlane_b32 s15, v239, 43
	v_lshrrev_b32_e32 v117, 5, v178
	v_and_b32_e32 v168, 31, v178
	v_lshlrev_b32_e32 v116, 2, v168
	v_mul_u32_u24_e32 v16, 0x204, v117
	v_lshl_add_u32 v16, v116, 2, v16
	v_and_b32_e32 v168, 7, v178
	v_lshlrev_b32_e32 v120, 4, v168
	v_mul_u32_u24_e32 v17, 0x1020, v168
	v_lshrrev_b32_e32 v119, 3, v178
	v_lshl_add_u32 v17, v119, 2, v17
	s_add_i32 s4, s56, 0
	s_mov_b32 s39, 0
	s_cmpk_lt_u32 s4, 0x6c0
	s_cbranch_scc0 .Ltrq6_t1_0
	s_lshr_b32 s5, s4, 5
	s_and_b32 s6, s4, 31
	v_readlane_b32 s28, v241, 11
	v_readlane_b32 s29, v241, 12
	s_mul_i32 s9, s8, 0x3430000
	s_movk_i32 s38, 0x6860
	s_mov_b32 s2, 0
	s_mul_i32 s3, s8, 0x1b00000
	s_movk_i32 s44, 0x1000
	s_mov_b32 s39, 1
	s_branch .Ltrq6_dec_0

.Ltrq6_nosc:
	v_mov_b32_e32 v168, v16
	ds_write2_b32 v168, v100, v101 offset1:1
	ds_write2_b32 v168, v102, v103 offset0:2 offset1:3
	v_add_u32_e32 v168, 8256, v16
	ds_write2_b32 v168, v104, v105 offset1:1
	ds_write2_b32 v168, v106, v107 offset0:2 offset1:3
	v_add_u32_e32 v168, 16512, v16
	ds_write2_b32 v168, v108, v109 offset1:1
	ds_write2_b32 v168, v110, v111 offset0:2 offset1:3
	v_add_u32_e32 v168, 24768, v16
	ds_write2_b32 v168, v112, v113 offset1:1
	ds_write2_b32 v168, v114, v115 offset0:2 offset1:3
	s_add_i32 s56, s56, 244
	s_cmpk_lt_u32 s56, 0x18e0
	s_cselect_b32 s7, 1, 0
	s_cbranch_scc0 .Ltrq6_nonext
	s_add_i32 s4, s56, 0
	s_mov_b32 s39, 0
	s_cmpk_lt_u32 s4, 0x6c0
	s_cbranch_scc0 .Ltrq6_t1_1
	s_lshr_b32 s5, s4, 5
	s_and_b32 s6, s4, 31
	v_readlane_b32 s28, v241, 11
	v_readlane_b32 s29, v241, 12
	s_mul_i32 s9, s8, 0x3430000
	s_movk_i32 s38, 0x6860
	s_mov_b32 s2, 0
	s_mul_i32 s3, s8, 0x1b00000
	s_movk_i32 s44, 0x1000
	s_mov_b32 s39, 1
	s_branch .Ltrq6_dec_1
